# P5 tail w_down conversion via shared conversion code; 192 GEMM CUs convert 1536 of the items after their last unit
# speedup vs baseline: 1.0123x; 1.0014x over previous
; #define LAS __attribute__((address_space(3)))
; __global__ void __launch_bounds__(NWAVES * 64, 2) fwd_kernel(Args args) {
;     extern __shared__ __attribute__((aligned(16))) unsigned char lds_raw[];
;     LAS unsigned char* lds = (LAS unsigned char*)lds_raw;
;     cg::grid_group grid = cg::this_grid();
;     const int tid = threadIdx.x, lane = tid & 63, wave = __builtin_amdgcn_readfirstlane(tid >> 6);
;     const int G = gridDim.x, bid = blockIdx.x;
;     const int gw = bid * NWAVES + wave, NGW = G * NWAVES;
;     const bool split_roles = (G == 256);
;     unsigned char* ws = args.ws;
;     volatile LAS unsigned* bst = (volatile LAS unsigned*)(lds + LDS_MISC);
;     if (tid == 0) { bst[0] = 0u; bst[1] = 0u; }
;     __syncthreads();
_Z10fwd_kernel4Args:
	s_load_dwordx8 s[56:63], s[0:1], 0x60
	s_load_dwordx8 s[4:11], s[0:1], 0x40
	s_load_dword s52, s[0:1], 0x80
	v_and_b32_e32 v195, 0x3ff, v0
	s_mov_b32 s48, s2
	s_mov_b32 s100, 0
	v_readfirstlane_b32 s24, v195
	s_waitcnt lgkmcnt(0)
	v_writelane_b32 v243, s4, 0
	v_cmp_eq_u32_e64 s[54:55], 0, v195
	s_nop 0
	v_writelane_b32 v243, s5, 1
	v_writelane_b32 v243, s6, 2
	v_writelane_b32 v243, s7, 3
	v_writelane_b32 v243, s8, 4
	v_writelane_b32 v243, s9, 5
	v_writelane_b32 v243, s10, 6
	v_writelane_b32 v243, s11, 7
	s_add_u32 s4, s0, 0x78
	s_addc_u32 s5, s1, 0
	s_and_saveexec_b64 s[2:3], s[54:55]
	s_cbranch_execz .LBB0_2
	s_add_i32 s6, 0, 0x23fc0
	v_mov_b32_e32 v1, 0
	v_mov_b32_e32 v2, s6
	s_add_i32 s6, 0, 0x23fc4
	ds_write_b32 v2, v1
	v_mov_b32_e32 v2, s6
	ds_write_b32 v2, v1

; __device__ __forceinline__ unsigned cvtpk(float lo, float hi) { f32x2_t v = {lo, hi}; bf16x2_t b = __builtin_convertvector(v, bf16x2_t); return __builtin_bit_cast(unsigned, b); }
; __global__ void __launch_bounds__(NWAVES * 64, 2) fwd_kernel(Args args) {
;     ...
;         for (int m = gw; m < SEQ; m += NGW) {
;             const f32x4* xr = (const f32x4*)(x + (size_t)m * DM) + lane; const f32x4* gr = (const f32x4*)norm1_g + lane;
;             f32x4 v[16]; float s = 0.f;
; #pragma unroll
;             for (int j = 0; j < 16; ++j) { v[j] = __builtin_nontemporal_load(xr + 64 * j); s += (v[j][0] * v[j][0] + v[j][1] * v[j][1]) + (v[j][2] * v[j][2] + v[j][3] * v[j][3]); }
;             const float rstd = __builtin_amdgcn_rsqf(wave_sum(s) * (1.0f / DM) + EPS);
;             u32x2* o8 = (u32x2*)(XN + (size_t)m * DM) + lane;
; #pragma unroll
;             for (int j = 0; j < 16; ++j) { const f32x4 gg = gr[64 * j]; const f32x4 y = v[j] * rstd * gg; u32x2 w; w.x = cvtpk(y[0], y[1]); w.y = cvtpk(y[2], y[3]); o8[64 * j] = w; }
;         }
.LBB0_92:
	s_cmp_eq_u32 s100, 1
	s_cbranch_scc1 .Lcvt_ret_p5
	s_cmpk_eq_i32 s24, 0x7b00
	s_cbranch_scc1 .Lcvt_ret_p1
	s_cmpk_gt_i32 s88, 0x1fff
	v_mbcnt_lo_u32_b32 v214, -1, 0
	s_waitcnt vmcnt(3)
	v_lshlrev_b32_e32 v196, 3, v212
	s_cbranch_scc1 .LBB0_95
	v_readlane_b32 s8, v243, 8
	v_lshlrev_b32_e32 v2, 4, v212
	v_mov_b32_e32 v3, 0
	v_readlane_b32 s10, v243, 10
	v_readlane_b32 s11, v243, 11
	s_mov_b64 s[2:3], 0x1000
	v_mbcnt_hi_u32_b32 v4, -1, v214
	v_lshl_add_u64 v[46:47], s[10:11], 0, v[2:3]
	v_lshl_add_u64 v[48:49], v[46:47], 0, s[2:3]
	s_mov_b64 s[2:3], 0x1400
	v_and_b32_e32 v1, 64, v4
	v_lshl_add_u64 v[50:51], v[46:47], 0, s[2:3]
	s_mov_b64 s[2:3], 0x1800
	v_add_u32_e32 v5, 64, v1
	v_xor_b32_e32 v1, 1, v4
	v_lshl_add_u64 v[52:53], v[46:47], 0, s[2:3]
	s_mov_b64 s[2:3], 0x1c00
	v_cmp_lt_i32_e32 vcc, v1, v5
	v_xor_b32_e32 v6, 2, v4
	v_lshl_add_u64 v[54:55], v[46:47], 0, s[2:3]
	s_mov_b64 s[2:3], 0x2000
	v_cndmask_b32_e32 v1, v4, v1, vcc
	v_cmp_lt_i32_e32 vcc, v6, v5
	v_lshl_add_u64 v[56:57], v[46:47], 0, s[2:3]
	s_mov_b64 s[2:3], 0x2400
	v_cndmask_b32_e32 v6, v4, v6, vcc
	v_lshl_add_u64 v[58:59], v[46:47], 0, s[2:3]
	s_mov_b64 s[2:3], 0x2800
	v_lshlrev_b32_e32 v76, 2, v6
	v_xor_b32_e32 v6, 4, v4
	v_lshl_add_u64 v[60:61], v[46:47], 0, s[2:3]
	s_mov_b64 s[2:3], 0x2c00
	v_cmp_lt_i32_e32 vcc, v6, v5
	s_waitcnt vmcnt(0)
	v_lshl_add_u64 v[62:63], v[46:47], 0, s[2:3]
	s_mov_b64 s[2:3], 0x3000
	v_cndmask_b32_e32 v6, v4, v6, vcc
	v_lshl_add_u64 v[64:65], v[46:47], 0, s[2:3]
	s_mov_b64 s[2:3], 0x3400
	v_lshlrev_b32_e32 v77, 2, v6
	v_xor_b32_e32 v6, 8, v4
	v_lshl_add_u64 v[66:67], v[46:47], 0, s[2:3]
	s_mov_b64 s[2:3], 0x3800
	v_cmp_lt_i32_e32 vcc, v6, v5
	v_lshl_add_u64 v[68:69], v[46:47], 0, s[2:3]
	s_mov_b64 s[2:3], 0x3c00
	s_ashr_i32 s89, s88, 31
	v_cndmask_b32_e32 v6, v4, v6, vcc
	v_lshl_add_u64 v[70:71], v[46:47], 0, s[2:3]
	s_lshl_b64 s[2:3], s[88:89], 14
	v_readlane_b32 s9, v243, 9
	v_lshlrev_b32_e32 v78, 2, v6
	v_xor_b32_e32 v6, 16, v4
	s_add_u32 s2, s8, s2
	v_cmp_lt_i32_e32 vcc, v6, v5
	s_addc_u32 s3, s9, s3
	s_ashr_i32 s1, s0, 31
	v_cndmask_b32_e32 v6, v4, v6, vcc
	v_lshl_add_u64 v[72:73], s[2:3], 0, v[2:3]
	s_lshl_b64 s[2:3], s[0:1], 14
	s_lshl_b64 s[6:7], s[88:89], 13
	v_lshlrev_b32_e32 v79, 2, v6
	v_xor_b32_e32 v6, 32, v4
	s_add_u32 s6, s60, s6
	v_cmp_lt_i32_e32 vcc, v6, v5
	v_mov_b32_e32 v197, v3
	s_addc_u32 s7, s61, s7
	v_cndmask_b32_e32 v4, v4, v6, vcc
	v_lshl_add_u64 v[2:3], s[6:7], 0, v[196:197]
	s_mov_b64 s[6:7], 0x14c00000
	v_lshlrev_b32_e32 v1, 2, v1
	v_lshlrev_b32_e32 v80, 2, v4
	v_lshl_add_u64 v[74:75], v[2:3], 0, s[6:7]
	s_lshl_b64 s[6:7], s[0:1], 13
	s_movk_i32 s1, 0x1000
	s_movk_i32 s8, 0x2000
	s_movk_i32 s9, 0x3000
	v_mov_b32_e32 v81, 0x358637bd
	s_mov_b32 s10, s88
	v_readlane_b32 s12, v243, 12
	v_readlane_b32 s13, v243, 13
	v_readlane_b32 s14, v243, 14
	v_readlane_b32 s15, v243, 15
	v_readlane_b32 s16, v243, 16
	v_readlane_b32 s17, v243, 17
	v_readlane_b32 s18, v243, 18
	v_readlane_b32 s19, v243, 19
	v_readlane_b32 s20, v243, 20
	v_readlane_b32 s21, v243, 21
	v_readlane_b32 s22, v243, 22
	v_readlane_b32 s23, v243, 23

; #define LAS __attribute__((address_space(3)))
; __global__ void __launch_bounds__(NWAVES * 64, 2) fwd_kernel(Args args) {
;     ...
;         {
;             const int nunits = (SEQ / 256) * (2 * DFF / 256), nfull = nunits % G;
;             if (!split_roles) {}
;             else if (nfull != 0 && bid >= nfull) cvt_range(args, CI_TOTAL - CI_D, CI_TOTAL, (bid - nfull) * NWAVES + wave, (G - nfull) * NWAVES, (LAS unsigned*)(lds + wave * 16384), lane);
;             else if (nfull == 0) cvt_range(args, CI_TOTAL - CI_D, CI_TOTAL, gw, NGW, (LAS unsigned*)(lds + wave * 16384), lane);
;         }
.LBB0_637:
	s_abs_i32 s2, s62
	v_cvt_f32_u32_e32 v0, s2
	s_sub_i32 s3, 0, s2
	s_mov_b32 s8, 0
	v_rcp_iflag_f32_e32 v0, v0
	s_nop 0
	v_mul_f32_e32 v0, 0x4f7ffffe, v0
	v_cvt_u32_f32_e32 v0, v0
	s_nop 0
	v_readfirstlane_b32 s4, v0
	s_mul_i32 s3, s3, s4
	s_mul_hi_u32 s3, s4, s3
	s_add_i32 s4, s4, s3
	s_mul_hi_u32 s3, s4, 0xac0
	s_mul_i32 s3, s3, s2
	s_sub_i32 s3, 0xac0, s3
	s_sub_i32 s4, s3, s2
	s_cmp_ge_u32 s3, s2
	s_cselect_b32 s3, s4, s3
	s_sub_i32 s4, s3, s2
	s_cmp_ge_u32 s3, s2
	s_cselect_b32 s2, s4, s3
	s_cmp_lt_i32 s55, s2
	v_readlane_b32 s4, v243, 27
	s_cselect_b64 s[2:3], -1, 0
	v_readlane_b32 s5, v243, 28
	s_or_b64 s[2:3], s[4:5], s[2:3]
	s_and_b64 vcc, exec, s[2:3]
	s_cbranch_vccnz .Lp5_nontail
	v_writelane_b32 v244, s0, 0
	v_writelane_b32 v244, s1, 1
	v_writelane_b32 v244, s46, 2
	v_writelane_b32 v244, s62, 3
	v_writelane_b32 v244, s64, 4
	v_writelane_b32 v244, s65, 5
	v_writelane_b32 v244, s66, 6
	v_writelane_b32 v244, s67, 7
	v_writelane_b32 v244, s68, 8
	v_writelane_b32 v244, s69, 9
	v_writelane_b32 v244, s70, 10
	v_writelane_b32 v244, s71, 11
	v_writelane_b32 v244, s88, 12
	v_writelane_b32 v244, s90, 13
	s_add_i32 s88, s94, 0x7500
	s_movk_i32 s62, 64
	s_mov_b32 s24, 0xa000
	s_branch .Lp5_call
.Lp5_nontail:
	s_and_b64 vcc, exec, s[4:5]
	s_cbranch_vccnz .LBB0_731
	v_writelane_b32 v244, s0, 0
	v_writelane_b32 v244, s1, 1
	v_writelane_b32 v244, s46, 2
	v_writelane_b32 v244, s62, 3
	v_writelane_b32 v244, s64, 4
	v_writelane_b32 v244, s65, 5
	v_writelane_b32 v244, s66, 6
	v_writelane_b32 v244, s67, 7
	v_writelane_b32 v244, s68, 8
	v_writelane_b32 v244, s69, 9
	v_writelane_b32 v244, s70, 10
	v_writelane_b32 v244, s71, 11
	v_writelane_b32 v244, s88, 12
	v_writelane_b32 v244, s90, 13
	s_add_i32 s88, s94, 0xa000
	s_movk_i32 s62, 192
	s_mov_b32 s24, 0xa600
.Lp5_call:
	s_and_b32 s90, s94, 7
	s_mov_b32 s100, 1
	s_branch .Lcvt_entry
.Lcvt_ret_p5:
	v_readlane_b32 s0, v244, 0
	v_readlane_b32 s1, v244, 1
	v_readlane_b32 s46, v244, 2
	v_readlane_b32 s62, v244, 3
	v_readlane_b32 s64, v244, 4
	v_readlane_b32 s65, v244, 5
	v_readlane_b32 s66, v244, 6
	v_readlane_b32 s67, v244, 7
	v_readlane_b32 s68, v244, 8
	v_readlane_b32 s69, v244, 9
	v_readlane_b32 s70, v244, 10
	v_readlane_b32 s71, v244, 11
	v_readlane_b32 s88, v244, 12
	v_readlane_b32 s90, v244, 13
	s_mov_b32 s100, 0
	v_lshlrev_b32_e32 v196, 3, v212
	s_nop 3
	s_branch .LBB0_731

; __global__ void __launch_bounds__(NWAVES * 64, 2) fwd_kernel(Args args) {
;     extern __shared__ __attribute__((aligned(16))) unsigned char lds_raw[];
	.amdhsa_kernel _Z10fwd_kernel4Args
		.amdhsa_group_segment_fixed_size 0
		.amdhsa_private_segment_fixed_size 0
		.amdhsa_kernarg_size 376
		.amdhsa_user_sgpr_count 2
		.amdhsa_user_sgpr_dispatch_ptr 0
		.amdhsa_user_sgpr_queue_ptr 0
		.amdhsa_user_sgpr_kernarg_segment_ptr 1
		.amdhsa_user_sgpr_dispatch_id 0
		.amdhsa_user_sgpr_kernarg_preload_length 0
		.amdhsa_user_sgpr_kernarg_preload_offset 0
		.amdhsa_user_sgpr_private_segment_size 0
		.amdhsa_uses_dynamic_stack 0
		.amdhsa_enable_private_segment 0
		.amdhsa_system_sgpr_workgroup_id_x 1
		.amdhsa_system_sgpr_workgroup_id_y 0
		.amdhsa_system_sgpr_workgroup_id_z 0
		.amdhsa_system_sgpr_workgroup_info 0
		.amdhsa_system_vgpr_workitem_id 2
		.amdhsa_next_free_vgpr 248
		.amdhsa_next_free_sgpr 102
		.amdhsa_accum_offset 248
		.amdhsa_reserve_vcc 1
		.amdhsa_float_round_mode_32 0
		.amdhsa_float_round_mode_16_64 0
		.amdhsa_float_denorm_mode_32 3
		.amdhsa_float_denorm_mode_16_64 3
		.amdhsa_dx10_clamp 1
		.amdhsa_ieee_mode 1
		.amdhsa_fp16_overflow 0
		.amdhsa_tg_split 0
		.amdhsa_exception_fp_ieee_invalid_op 0
		.amdhsa_exception_fp_denorm_src 0
		.amdhsa_exception_fp_ieee_div_zero 0
		.amdhsa_exception_fp_ieee_overflow 0
		.amdhsa_exception_fp_ieee_underflow 0
		.amdhsa_exception_fp_ieee_inexact 0
		.amdhsa_exception_int_div_zero 0
	.end_amdhsa_kernel

; __global__ void __launch_bounds__(NWAVES * 64, 2) fwd_kernel(Args args) {
;     extern __shared__ __attribute__((aligned(16))) unsigned char lds_raw[];
amdhsa.kernels:
  - .agpr_count:     0
    .args:
      - .offset:         0
        .size:           120
        .value_kind:     by_value
      - .offset:         120
        .size:           4
        .value_kind:     hidden_block_count_x
      - .offset:         124
        .size:           4
        .value_kind:     hidden_block_count_y
      - .offset:         128
        .size:           4
        .value_kind:     hidden_block_count_z
      - .offset:         132
        .size:           2
        .value_kind:     hidden_group_size_x
      - .offset:         134
        .size:           2
        .value_kind:     hidden_group_size_y
      - .offset:         136
        .size:           2
        .value_kind:     hidden_group_size_z
      - .offset:         138
        .size:           2
        .value_kind:     hidden_remainder_x
      - .offset:         140
        .size:           2
        .value_kind:     hidden_remainder_y
      - .offset:         142
        .size:           2
        .value_kind:     hidden_remainder_z
      - .offset:         160
        .size:           8
        .value_kind:     hidden_global_offset_x
      - .offset:         168
        .size:           8
        .value_kind:     hidden_global_offset_y
      - .offset:         176
        .size:           8
        .value_kind:     hidden_global_offset_z
      - .offset:         184
        .size:           2
        .value_kind:     hidden_grid_dims
      - .offset:         208
        .size:           8
        .value_kind:     hidden_multigrid_sync_arg
      - .offset:         240
        .size:           4
        .value_kind:     hidden_dynamic_lds_size
    .group_segment_fixed_size: 0
    .kernarg_segment_align: 8
    .kernarg_segment_size: 376
    .language:       OpenCL C
    .language_version:
      - 2
      - 0
    .max_flat_workgroup_size: 512
    .name:           _Z10fwd_kernel4Args
    .private_segment_fixed_size: 0
    .sgpr_count:     108
    .sgpr_spill_count: 71
    .symbol:         _Z10fwd_kernel4Args.kd
    .uniform_work_group_size: 1
    .uses_dynamic_stack: false
    .vgpr_count:     248
    .vgpr_spill_count: 0
    .wavefront_size: 64
